# chunk MLP: keep g_v in registers instead of 3 reloads+waits per task; hoist 2nd bias load above the stores
# baseline (speedup 1.0000x reference)
.LBB0_349:
	v_or_b32_e32 v0, s50, v20
	v_mov_b64_e32 v[54:55], s[46:47]
	s_mul_i32 s33, s51, 0x3400
	v_mad_u64_u32 v[0:1], s[4:5], v0, s54, v[54:55]
	v_add_u32_e32 v1, s33, v1
	s_lshl_b32 s16, s52, 8
	v_or_b32_e32 v2, s50, v28
	v_lshl_add_u64 v[0:1], v[0:1], 0, s[16:17]
	v_mad_u64_u32 v[2:3], s[4:5], v2, s54, v[54:55]
	v_lshl_add_u64 v[0:1], v[0:1], 0, v[22:23]
	v_add_u32_e32 v3, s33, v3
	v_add_co_u32_e32 v0, vcc, s27, v0
	v_lshl_add_u64 v[2:3], v[2:3], 0, s[16:17]
	s_nop 0
	v_addc_co_u32_e32 v1, vcc, 0, v1, vcc
	v_lshl_add_u64 v[2:3], v[2:3], 0, v[22:23]
	v_add_co_u32_e32 v2, vcc, s27, v2
	v_mov_b32_e32 v51, v23
	s_nop 0
	v_addc_co_u32_e32 v3, vcc, 0, v3, vcc
	flat_load_dwordx4 v[4:7], v[0:1] offset:3072
	flat_load_dwordx4 v[8:11], v[2:3] offset:3072
	v_lshl_add_u64 v[2:3], s[50:51], 0, v[32:33]
	v_mad_u64_u32 v[16:17], s[4:5], v2, s54, v[54:55]
	v_mov_b32_e32 v2, v17
	v_mad_u64_u32 v[2:3], s[4:5], v3, s54, v[2:3]
	v_or_b32_e32 v0, s50, v30
	v_mov_b32_e32 v17, v2
	v_mad_u64_u32 v[0:1], s[4:5], v0, s54, v[54:55]
	v_lshl_add_u64 v[2:3], v[16:17], 0, s[16:17]
	v_lshl_add_u64 v[16:17], s[50:51], 0, v[26:27]
	v_add_u32_e32 v1, s33, v1
	v_mad_u64_u32 v[18:19], s[4:5], v16, s54, v[54:55]
	v_lshl_add_u64 v[0:1], v[0:1], 0, s[16:17]
	v_mov_b32_e32 v16, v19
	v_lshl_add_u64 v[0:1], v[0:1], 0, v[22:23]
	v_mad_u64_u32 v[16:17], s[4:5], v17, s54, v[16:17]
	v_add_co_u32_e32 v0, vcc, s27, v0
	v_mov_b32_e32 v19, v16
	s_nop 0
	v_addc_co_u32_e32 v1, vcc, 0, v1, vcc
	v_lshl_add_u64 v[2:3], v[2:3], 0, v[22:23]
	v_lshl_add_u64 v[16:17], v[18:19], 0, s[16:17]
	v_add_co_u32_e32 v2, vcc, s27, v2
	v_mov_b32_e32 v53, v23
	v_lshl_add_u64 v[16:17], v[16:17], 0, v[50:51]
	v_addc_co_u32_e32 v3, vcc, 0, v3, vcc
	v_lshl_add_u64 v[16:17], v[16:17], 0, v[52:53]
	v_add_co_u32_e32 v62, vcc, s27, v16
	v_lshl_add_u64 v[60:61], v[16:17], 0, s[22:23]
	s_nop 0
	v_addc_co_u32_e32 v63, vcc, 0, v17, vcc
	v_lshl_add_u64 v[64:65], v[16:17], 0, s[24:25]
	v_add_co_u32_e32 v16, vcc, s57, v16
	s_lshl_b32 s4, s52, 9
	s_nop 0
	v_addc_co_u32_e32 v17, vcc, 0, v17, vcc
	s_mov_b32 s5, s17
	flat_load_dwordx4 v[112:115], v[0:1] offset:3072
	s_nop 0
	flat_load_dwordx4 v[0:3], v[2:3] offset:3072
	s_nop 0
	flat_load_dwordx2 v[72:73], v[62:63] offset:1024
	flat_load_dwordx2 v[70:71], v[60:61] offset:32
	flat_load_dwordx2 v[68:69], v[60:61] offset:64
	flat_load_dwordx2 v[66:67], v[60:61] offset:96
	flat_load_dwordx2 v[58:59], v[16:17] offset:1024
	flat_load_dwordx2 v[56:57], v[64:65] offset:32
	flat_load_dwordx2 v[18:19], v[64:65] offset:64
	s_nop 0
	flat_load_dwordx2 v[16:17], v[64:65] offset:96
	v_lshl_add_u64 v[64:65], v[14:15], 0, s[4:5]
	s_waitcnt lgkmcnt(0)
	s_barrier
	flat_load_dwordx4 v[116:119], v[64:65]
	flat_load_dwordx4 v[120:123], v[64:65] offset:16
	ds_read_b32 v43, v25
	ds_read_b32 v47, v94
	ds_read_b32 v49, v97
	ds_read_b32 v111, v100
	s_add_i32 s60, s60, s38
	s_add_i32 s59, s59, s39
	s_cmpk_lt_i32 s60, 0x1000
	s_waitcnt vmcnt(0)
	v_mov_b32_e32 v208, v116
	v_mov_b32_e32 v209, v117
	v_mov_b32_e32 v210, v118
	v_mov_b32_e32 v211, v119
	v_mov_b32_e32 v212, v120
	v_mov_b32_e32 v213, v121
	v_mov_b32_e32 v214, v122
	v_mov_b32_e32 v215, v123
	v_lshlrev_b32_e32 v45, 16, v4
	v_and_b32_e32 v4, 0xffff0000, v4
	s_waitcnt lgkmcnt(0)
	v_mul_f32_e32 v4, v43, v4
	v_mul_f32_e32 v45, v43, v45
	v_lshlrev_b32_e32 v74, 16, v5
	v_and_b32_e32 v5, 0xffff0000, v5
	v_mul_f32_e32 v74, v43, v74
	v_mul_f32_e32 v5, v43, v5
	v_lshlrev_b32_e32 v75, 16, v6
	v_and_b32_e32 v6, 0xffff0000, v6
	v_mul_f32_e32 v75, v43, v75
	v_mul_f32_e32 v6, v43, v6
	v_lshlrev_b32_e32 v176, 16, v70
	v_and_b32_e32 v177, 0xffff0000, v70
	v_lshlrev_b32_e32 v178, 16, v71
	v_and_b32_e32 v179, 0xffff0000, v71
	v_lshlrev_b32_e32 v182, 16, v69
	v_and_b32_e32 v183, 0xffff0000, v69
	v_lshlrev_b32_e32 v180, 16, v68
	v_mul_f32_e32 v4, v4, v117
	v_mul_f32_e32 v45, v45, v116
	v_cvt_pk_bf16_f32 v4, v45, v4
	v_mul_f32_e32 v74, v74, v118
	v_mul_f32_e32 v5, v5, v119
	v_lshlrev_b32_e32 v116, 16, v7
	v_and_b32_e32 v7, 0xffff0000, v7
	ds_write_b16 v29, v4 offset:34816
	ds_write_b16_d16_hi v31, v4 offset:35088
	v_cvt_pk_bf16_f32 v4, v74, v5
	v_mul_f32_e32 v75, v75, v120
	v_mul_f32_e32 v6, v6, v121
	v_mul_f32_e32 v116, v43, v116
	v_mul_f32_e32 v7, v43, v7
	ds_write_b16 v29, v4 offset:35360
	ds_write_b16_d16_hi v31, v4 offset:35632
	v_cvt_pk_bf16_f32 v4, v75, v6
	v_mul_f32_e32 v116, v116, v122
	v_mul_f32_e32 v7, v7, v123
	ds_write_b16 v29, v4 offset:35904
	ds_write_b16_d16_hi v31, v4 offset:36176
	v_cvt_pk_bf16_f32 v4, v116, v7
	ds_write_b16 v29, v4 offset:36448
	ds_write_b16_d16_hi v31, v4 offset:36720
	s_nop 1
	v_mov_b64_e32 v[4:5], v[208:209]
	v_mov_b64_e32 v[6:7], v[210:211]
	s_nop 1
	v_mov_b64_e32 v[116:117], v[212:213]
	v_mov_b64_e32 v[118:119], v[214:215]
	v_lshlrev_b32_e32 v43, 16, v8
	v_and_b32_e32 v8, 0xffff0000, v8
	v_lshlrev_b32_e32 v45, 16, v9
	v_and_b32_e32 v9, 0xffff0000, v9
	v_mul_f32_e32 v43, v47, v43
	v_lshlrev_b32_e32 v74, 16, v10
	v_and_b32_e32 v10, 0xffff0000, v10
	v_lshlrev_b32_e32 v75, 16, v11
	v_and_b32_e32 v11, 0xffff0000, v11
	v_mul_f32_e32 v8, v47, v8
	v_mul_f32_e32 v45, v47, v45
	v_mul_f32_e32 v9, v47, v9
	v_mul_f32_e32 v74, v47, v74
	v_mul_f32_e32 v10, v47, v10
	v_mul_f32_e32 v75, v47, v75
	v_mul_f32_e32 v11, v47, v11
	v_lshlrev_b32_e32 v47, 16, v113
	v_mul_f32_e32 v47, v49, v47
	v_lshlrev_b32_e32 v120, 16, v2
	v_and_b32_e32 v121, 0xffff0000, v2
	v_lshlrev_b32_e32 v122, 16, v3
	v_and_b32_e32 v123, 0xffff0000, v3
	v_mul_f32_e32 v124, v111, v120
	v_mul_f32_e32 v125, v111, v121
	v_mul_f32_e32 v122, v111, v122
	v_and_b32_e32 v181, 0xffff0000, v68
	v_lshlrev_b32_e32 v184, 16, v66
	v_and_b32_e32 v185, 0xffff0000, v66
	v_lshlrev_b32_e32 v186, 16, v67
	v_and_b32_e32 v187, 0xffff0000, v67
	v_pk_mul_f32 v[66:67], v[176:177], v[176:177]
	v_pk_mul_f32 v[68:69], v[178:179], v[178:179]
	v_pk_mul_f32 v[70:71], v[180:181], v[180:181]
	s_nop 0
	v_mul_f32_e32 v4, v43, v4
	v_mul_f32_e32 v5, v8, v5
	v_mul_f32_e32 v6, v45, v6
	v_mul_f32_e32 v7, v9, v7
	v_cvt_pk_bf16_f32 v4, v4, v5
	v_mul_f32_e32 v8, v74, v116
	v_mul_f32_e32 v9, v10, v117
	v_mul_f32_e32 v10, v75, v118
	v_mul_f32_e32 v11, v11, v119
	v_cvt_pk_bf16_f32 v5, v6, v7
	v_cvt_pk_bf16_f32 v6, v8, v9
	v_cvt_pk_bf16_f32 v7, v10, v11
	ds_write_b16 v95, v4 offset:34816
	ds_write_b16_d16_hi v96, v4 offset:35088
	ds_write_b16 v95, v5 offset:35360
	ds_write_b16_d16_hi v96, v5 offset:35632
	ds_write_b16 v95, v6 offset:35904
	ds_write_b16_d16_hi v96, v6 offset:36176
	ds_write_b16 v95, v7 offset:36448
	ds_write_b16_d16_hi v96, v7 offset:36720
	s_nop 1
	v_mov_b64_e32 v[4:5], v[208:209]
	v_mov_b64_e32 v[6:7], v[210:211]
	s_nop 1
	v_mov_b64_e32 v[8:9], v[212:213]
	v_mov_b64_e32 v[10:11], v[214:215]
	v_lshlrev_b32_e32 v43, 16, v112
	v_and_b32_e32 v45, 0xffff0000, v112
	v_and_b32_e32 v74, 0xffff0000, v113
	v_mul_f32_e32 v43, v49, v43
	v_lshlrev_b32_e32 v75, 16, v114
	v_and_b32_e32 v112, 0xffff0000, v114
	v_lshlrev_b32_e32 v113, 16, v115
	v_and_b32_e32 v114, 0xffff0000, v115
	v_mul_f32_e32 v45, v49, v45
	v_mul_f32_e32 v74, v49, v74
	v_mul_f32_e32 v75, v49, v75
	v_mul_f32_e32 v112, v49, v112
	v_mul_f32_e32 v113, v49, v113
	v_mul_f32_e32 v49, v49, v114
	v_pk_mul_f32 v[114:115], v[182:183], v[182:183]
	v_pk_mul_f32 v[118:119], v[186:187], v[186:187]
	v_pk_mul_f32 v[116:117], v[184:185], v[184:185]
	s_nop 0
	v_mul_f32_e32 v4, v43, v4
	v_mul_f32_e32 v5, v45, v5
	v_mul_f32_e32 v6, v47, v6
	v_mul_f32_e32 v7, v74, v7
	v_cvt_pk_bf16_f32 v4, v4, v5
	v_mul_f32_e32 v8, v75, v8
	v_mul_f32_e32 v9, v112, v9
	v_mul_f32_e32 v10, v113, v10
	v_mul_f32_e32 v11, v49, v11
	v_cvt_pk_bf16_f32 v5, v6, v7
	v_cvt_pk_bf16_f32 v6, v8, v9
	v_cvt_pk_bf16_f32 v7, v10, v11
	ds_write_b16 v98, v4 offset:34816
	ds_write_b16_d16_hi v99, v4 offset:35088
	ds_write_b16 v98, v5 offset:35360
	ds_write_b16_d16_hi v99, v5 offset:35632
	ds_write_b16 v98, v6 offset:35904
	ds_write_b16_d16_hi v99, v6 offset:36176
	ds_write_b16 v98, v7 offset:36448
	ds_write_b16_d16_hi v99, v7 offset:36720
	s_nop 1
	v_mov_b64_e32 v[8:9], v[208:209]
	v_mov_b64_e32 v[10:11], v[210:211]
	s_nop 1
	v_mov_b64_e32 v[4:5], v[212:213]
	v_mov_b64_e32 v[6:7], v[214:215]
	v_or_b32_e32 v43, s52, v92
	v_mov_b32_e32 v75, v23
	v_lshlrev_b32_e32 v74, 2, v43
	v_lshl_add_u64 v[112:113], s[36:37], 0, v[74:75]
	v_lshlrev_b32_e32 v74, 16, v72
	v_and_b32_e32 v75, 0xffff0000, v72
	v_lshlrev_b32_e32 v72, 16, v73
	v_and_b32_e32 v73, 0xffff0000, v73
	v_mov_b64_e32 v[64:65], s[28:29]
	v_pk_mul_f32 v[2:3], v[72:73], v[72:73]
	v_lshlrev_b32_e32 v43, 16, v0
	v_pk_fma_f32 v[2:3], v[2:3], s[26:27], v[64:65] op_sel_hi:[1,0,0] neg_lo:[1,0,0] neg_hi:[1,0,0]
	v_and_b32_e32 v45, 0xffff0000, v0
	v_mul_f32_e32 v43, v111, v43
	v_pk_mul_f32 v[2:3], v[2:3], v[72:73]
	v_lshlrev_b32_e32 v47, 16, v1
	v_and_b32_e32 v49, 0xffff0000, v1
	v_mul_f32_e32 v45, v111, v45
	v_exp_f32_e32 v120, v2
	v_mul_f32_e32 v47, v111, v47
	v_mul_f32_e32 v49, v111, v49
	v_mul_f32_e32 v111, v111, v123
	v_exp_f32_e32 v121, v3
	v_pk_mul_f32 v[0:1], v[74:75], v[74:75]
	v_pk_fma_f32 v[66:67], v[66:67], s[26:27], v[64:65] op_sel_hi:[1,0,0] neg_lo:[1,0,0] neg_hi:[1,0,0]
	v_pk_fma_f32 v[0:1], v[0:1], s[26:27], v[64:65] op_sel_hi:[1,0,0] neg_lo:[1,0,0] neg_hi:[1,0,0]
	v_pk_fma_f32 v[68:69], v[68:69], s[26:27], v[64:65] op_sel_hi:[1,0,0] neg_lo:[1,0,0] neg_hi:[1,0,0]
	v_pk_fma_f32 v[114:115], v[114:115], s[26:27], v[64:65] op_sel_hi:[1,0,0] neg_lo:[1,0,0] neg_hi:[1,0,0]
	v_pk_mul_f32 v[0:1], v[0:1], v[74:75]
	v_pk_mul_f32 v[66:67], v[66:67], v[176:177]
	v_pk_mul_f32 v[68:69], v[68:69], v[178:179]
	v_pk_mul_f32 v[114:115], v[114:115], v[182:183]
	v_exp_f32_e32 v0, v0
	v_exp_f32_e32 v1, v1
	v_exp_f32_e32 v66, v66
	v_exp_f32_e32 v67, v67
	v_exp_f32_e32 v68, v68
	v_exp_f32_e32 v69, v69
	v_exp_f32_e32 v123, v115
	v_pk_fma_f32 v[118:119], v[118:119], s[26:27], v[64:65] op_sel_hi:[1,0,0] neg_lo:[1,0,0] neg_hi:[1,0,0]
	v_pk_add_f32 v[136:137], v[0:1], 1.0 op_sel_hi:[1,0]
	v_pk_mul_f32 v[118:119], v[118:119], v[186:187]
	v_pk_add_f32 v[140:141], v[120:121], 1.0 op_sel_hi:[1,0]
	v_exp_f32_e32 v128, v118
	v_exp_f32_e32 v129, v119
	v_pk_add_f32 v[144:145], v[66:67], 1.0 op_sel_hi:[1,0]
	v_pk_add_f32 v[148:149], v[68:69], 1.0 op_sel_hi:[1,0]
	v_pk_fma_f32 v[116:117], v[116:117], s[26:27], v[64:65] op_sel_hi:[1,0,0] neg_lo:[1,0,0] neg_hi:[1,0,0]
	v_pk_add_f32 v[172:173], v[128:129], 1.0 op_sel_hi:[1,0]
	v_pk_mul_f32 v[116:117], v[116:117], v[184:185]
	v_rcp_f32_e32 v174, v136
	v_rcp_f32_e32 v175, v137
	v_rcp_f32_e32 v188, v140
	v_rcp_f32_e32 v189, v141
	v_rcp_f32_e32 v190, v144
	v_rcp_f32_e32 v191, v145
	v_rcp_f32_e32 v192, v148
	v_rcp_f32_e32 v193, v149
	v_pk_fma_f32 v[70:71], v[70:71], s[26:27], v[64:65] op_sel_hi:[1,0,0] neg_lo:[1,0,0] neg_hi:[1,0,0]
	v_rcp_f32_e32 v202, v172
	v_pk_mul_f32 v[70:71], v[70:71], v[180:181]
	v_rcp_f32_e32 v203, v173
	v_exp_f32_e32 v70, v70
	v_exp_f32_e32 v71, v71
	v_pk_mul_f32 v[74:75], v[174:175], v[74:75]
	v_pk_mul_f32 v[204:205], v[188:189], v[72:73]
	v_pk_mul_f32 v[206:207], v[190:191], v[176:177]
	v_pk_add_f32 v[70:71], v[70:71], 1.0 op_sel_hi:[1,0]
	v_pk_mul_f32 v[192:193], v[192:193], v[178:179]
	v_rcp_f32_e32 v194, v70
	v_rcp_f32_e32 v195, v71
	v_pk_mul_f32 v[202:203], v[202:203], v[186:187]
	v_pk_mul_f32 v[194:195], v[194:195], v[180:181]
	s_nop 0
	v_mul_f32_e32 v2, v43, v8
	v_mul_f32_e32 v3, v45, v9
	v_mul_f32_e32 v4, v124, v4
	v_mul_f32_e32 v5, v125, v5
	v_cvt_pk_bf16_f32 v2, v2, v3
	v_mul_f32_e32 v8, v47, v10
	v_mul_f32_e32 v9, v49, v11
	v_mul_f32_e32 v6, v122, v6
	v_mul_f32_e32 v7, v111, v7
	v_cvt_pk_bf16_f32 v3, v8, v9
	v_cvt_pk_bf16_f32 v4, v4, v5
	v_cvt_pk_bf16_f32 v5, v6, v7
	ds_write_b16 v101, v2 offset:34816
	ds_write_b16_d16_hi v102, v2 offset:35088
	ds_write_b16 v101, v3 offset:35360
	ds_write_b16_d16_hi v102, v3 offset:35632
	ds_write_b16 v101, v4 offset:35904
	ds_write_b16_d16_hi v102, v4 offset:36176
	ds_write_b16 v101, v5 offset:36448
	ds_write_b16_d16_hi v102, v5 offset:36720
	s_waitcnt lgkmcnt(0)
	s_barrier
	flat_load_dword v43, v[112:113]
	v_or_b32_e32 v216, s52, v93
	v_lshlrev_b32_e32 v216, 2, v216
	v_mov_b32_e32 v217, 0
	v_lshl_add_u64 v[216:217], s[36:37], 0, v[216:217]
	global_load_dword v218, v[216:217], off
	v_exp_f32_e32 v122, v114
	ds_read_b128 v[0:3], v76 offset:34816
	ds_read_b128 v[4:7], v110
	ds_read_b128 v[8:11], v77 offset:34816
	ds_read_b128 v[66:69], v78 offset:34816
	ds_read_b128 v[112:115], v110 offset:64
	v_pk_add_f32 v[164:165], v[122:123], 1.0 op_sel_hi:[1,0]
	ds_read_b128 v[120:123], v79 offset:34816
	ds_read_b128 v[128:131], v80 offset:34816
	ds_read_b128 v[136:139], v81 offset:34816
	ds_read_b128 v[140:143], v82 offset:34816
	ds_read_b128 v[144:147], v83 offset:34816
	ds_read_b128 v[148:151], v84 offset:34816
	v_exp_f32_e32 v124, v116
	v_exp_f32_e32 v125, v117
	s_waitcnt lgkmcnt(0)
	v_mfma_f32_16x16x32_bf16 v[116:119], v[0:3], v[4:7], 0
	ds_read_b128 v[152:155], v110 offset:128
	ds_read_b128 v[156:159], v85 offset:34816
	v_rcp_f32_e32 v198, v164
	v_pk_add_f32 v[168:169], v[124:125], 1.0 op_sel_hi:[1,0]
	v_mfma_f32_16x16x32_bf16 v[124:127], v[8:11], v[4:7], 0
	v_rcp_f32_e32 v199, v165
	v_rcp_f32_e32 v200, v168
	v_rcp_f32_e32 v201, v169
	v_mfma_f32_16x16x32_bf16 v[132:135], v[66:69], v[4:7], 0
	v_mul_f32_e64 v198, v198, v182
	v_mul_f32_e64 v199, v199, v183
	v_pk_mul_f32 v[200:201], v[200:201], v[184:185]
	v_mfma_f32_16x16x32_bf16 v[4:7], v[120:123], v[4:7], 0
	v_mfma_f32_16x16x32_bf16 v[116:119], v[128:131], v[112:115], v[116:119]
	v_mfma_f32_16x16x32_bf16 v[124:127], v[136:139], v[112:115], v[124:127]
	v_mfma_f32_16x16x32_bf16 v[132:135], v[140:143], v[112:115], v[132:135]
	v_mfma_f32_16x16x32_bf16 v[4:7], v[144:147], v[112:115], v[4:7]
	ds_read_b128 v[112:115], v86 offset:34816
	ds_read_b128 v[160:163], v110 offset:192
	ds_read_b128 v[164:167], v87 offset:34816
	ds_read_b128 v[168:171], v88 offset:34816
	s_waitcnt lgkmcnt(0)
	v_mfma_f32_16x16x32_bf16 v[116:119], v[148:151], v[152:155], v[116:119]
	ds_read_b128 v[172:175], v89 offset:34816
	ds_read_b128 v[70:73], v90 offset:34816
	v_mfma_f32_16x16x32_bf16 v[124:127], v[156:159], v[152:155], v[124:127]
	v_mfma_f32_16x16x32_bf16 v[132:135], v[112:115], v[152:155], v[132:135]
	v_mfma_f32_16x16x32_bf16 v[4:7], v[164:167], v[152:155], v[4:7]
	ds_read_b128 v[152:155], v91 offset:34816
	ds_read_b128 v[176:179], v110 offset:4352
	ds_read_b128 v[180:183], v110 offset:4416
	ds_read_b128 v[184:187], v110 offset:4480
	ds_read_b128 v[188:191], v110 offset:4544
	v_mfma_f32_16x16x32_bf16 v[116:119], v[168:171], v[160:163], v[116:119]
	s_waitcnt lgkmcnt(0)
	v_mfma_f32_16x16x32_bf16 v[124:127], v[172:175], v[160:163], v[124:127]
	v_mfma_f32_16x16x32_bf16 v[132:135], v[70:73], v[160:163], v[132:135]
	s_waitcnt vmcnt(0)
	s_nop 3
	v_add_f32_e32 v45, v116, v43
	v_mfma_f32_16x16x32_bf16 v[4:7], v[152:155], v[160:163], v[4:7]
	v_add_f32_e32 v47, v117, v43
	v_add_f32_e32 v49, v118, v43
	v_add_f32_e32 v111, v119, v43
	v_add_f32_e32 v116, v124, v43
	v_add_f32_e32 v117, v125, v43
	v_add_f32_e32 v118, v126, v43
	v_add_f32_e32 v119, v127, v43
	v_add_f32_e32 v125, v133, v43
	v_add_f32_e32 v126, v134, v43
	v_add_f32_e32 v4, v4, v43
	v_add_f32_e32 v5, v5, v43
	v_add_f32_e32 v124, v132, v43
	v_add_f32_e32 v127, v135, v43
	v_add_f32_e32 v6, v6, v43
	v_add_f32_e32 v7, v7, v43
	v_mul_f32_e32 v43, v74, v45
	v_mul_f32_e32 v45, v75, v47
	v_mul_f32_e32 v47, v204, v49
	v_mul_f32_e32 v49, v205, v111
	v_mul_f32_e32 v74, v206, v116
	v_mul_f32_e32 v75, v207, v117
	v_mul_f32_e32 v111, v192, v118
	v_mul_f32_e32 v116, v193, v119
	v_mul_f32_e32 v118, v195, v125
	v_mul_f32_e32 v119, v198, v126
	v_mul_f32_e32 v125, v200, v4
	v_mul_f32_e32 v126, v201, v5
	v_cvt_pk_bf16_f32 v4, v43, v45
	v_cvt_pk_bf16_f32 v5, v47, v49
	v_mul_f32_e32 v117, v194, v124
	v_mul_f32_e32 v124, v199, v127
	v_mul_f32_e32 v127, v202, v6
	v_mul_f32_e32 v132, v203, v7
	v_cvt_pk_bf16_f32 v6, v74, v75
	v_cvt_pk_bf16_f32 v7, v111, v116
	v_cvt_pk_bf16_f32 v74, v117, v118
	v_cvt_pk_bf16_f32 v75, v119, v124
	flat_store_dwordx2 v[62:63], v[4:5] offset:1024
	flat_store_dwordx2 v[60:61], v[6:7] offset:32
	flat_store_dwordx2 v[60:61], v[74:75] offset:64
	v_or_b32_e32 v4, s52, v93
	v_lshlrev_b32_e32 v4, 2, v4
	v_mov_b32_e32 v5, v23
	v_cvt_pk_bf16_f32 v116, v125, v126
	v_cvt_pk_bf16_f32 v117, v127, v132
	flat_store_dwordx2 v[60:61], v[116:117] offset:96
	v_lshl_add_u64 v[4:5], s[36:37], 0, v[4:5]
	v_mov_b32_e32 v43, v218
	v_lshl_add_u64 v[6:7], s[50:51], 0, v[34:35]
	v_mfma_f32_16x16x32_bf16 v[2:5], v[0:3], v[176:179], 0
	v_mad_u64_u32 v[54:55], s[4:5], v6, s54, v[54:55]
	v_mov_b32_e32 v6, v55
	v_mfma_f32_16x16x32_bf16 v[60:63], v[66:69], v[176:179], 0
	v_mad_u64_u32 v[0:1], s[4:5], v7, s54, v[6:7]
	v_lshlrev_b32_e32 v74, 16, v58
	v_mfma_f32_16x16x32_bf16 v[66:69], v[120:123], v[176:179], 0
	v_and_b32_e32 v75, 0xffff0000, v58
	v_lshlrev_b32_e32 v116, 16, v59
	v_and_b32_e32 v117, 0xffff0000, v59
	v_mov_b32_e32 v55, v0
	v_mfma_f32_16x16x32_bf16 v[6:9], v[8:11], v[176:179], 0
	v_mul_f32_e64 v58, v74, v74
	v_mul_f32_e64 v59, v75, v75
	v_pk_mul_f32 v[122:123], v[116:117], v[116:117]
	v_lshl_add_u64 v[0:1], v[54:55], 0, s[16:17]
	v_mfma_f32_16x16x32_bf16 v[2:5], v[128:131], v[180:183], v[2:5]
	v_lshlrev_b32_e32 v118, 16, v56
	v_and_b32_e32 v119, 0xffff0000, v56
	v_lshlrev_b32_e32 v120, 16, v57
	v_and_b32_e32 v121, 0xffff0000, v57
	v_mfma_f32_16x16x32_bf16 v[54:57], v[140:143], v[180:183], v[60:63]
	v_fma_f32 v122, -v122, s26, v64
	v_fma_f32 v123, -v123, s26, v64
	v_pk_mul_f32 v[124:125], v[118:119], v[118:119]
	v_pk_mul_f32 v[126:127], v[120:121], v[120:121]
	v_pk_fma_f32 v[62:63], v[58:59], s[26:27], v[64:65] op_sel_hi:[1,0,0] neg_lo:[1,0,0] neg_hi:[1,0,0]
	v_mfma_f32_16x16x32_bf16 v[58:61], v[144:147], v[180:183], v[66:69]
	v_mul_f32_e64 v62, v62, v74
	v_mul_f32_e64 v63, v63, v75
	v_pk_fma_f32 v[124:125], v[124:125], s[26:27], v[64:65] op_sel_hi:[1,0,0] neg_lo:[1,0,0] neg_hi:[1,0,0]
	v_exp_f32_e32 v62, v62
	v_pk_mul_f32 v[68:69], v[122:123], v[116:117]
	v_exp_f32_e32 v63, v63
	v_exp_f32_e32 v68, v68
	v_exp_f32_e32 v69, v69
	v_mfma_f32_16x16x32_bf16 v[6:9], v[136:139], v[180:183], v[6:9]
	v_mul_f32_e64 v122, v124, v118
	v_mul_f32_e64 v123, v125, v119
	v_pk_add_f32 v[62:63], v[62:63], 1.0 op_sel_hi:[1,0]
	v_pk_add_f32 v[68:69], v[68:69], 1.0 op_sel_hi:[1,0]
	v_mfma_f32_16x16x32_bf16 v[2:5], v[148:151], v[184:187], v[2:5]
	v_fma_f32 v66, -v126, s26, v64
	v_fma_f32 v67, -v127, s26, v64
	v_rcp_f32_e32 v62, v62
	v_rcp_f32_e32 v63, v63
	v_mfma_f32_16x16x32_bf16 v[54:57], v[112:115], v[184:187], v[54:57]
	v_exp_f32_e32 v112, v122
	v_exp_f32_e32 v113, v123
	v_rcp_f32_e32 v68, v68
	v_mfma_f32_16x16x32_bf16 v[6:9], v[156:159], v[184:187], v[6:9]
	v_rcp_f32_e32 v69, v69
	v_pk_mul_f32 v[66:67], v[66:67], v[120:121]
	v_pk_add_f32 v[112:113], v[112:113], 1.0 op_sel_hi:[1,0]
	v_mfma_f32_16x16x32_bf16 v[2:5], v[168:171], v[188:191], v[2:5]
	v_exp_f32_e32 v66, v66
	v_exp_f32_e32 v67, v67
	v_lshl_add_u64 v[0:1], v[0:1], 0, v[50:51]
	v_mfma_f32_16x16x32_bf16 v[6:9], v[172:175], v[188:191], v[6:9]
	v_rcp_f32_e32 v112, v112
	v_rcp_f32_e32 v113, v113
	v_pk_mul_f32 v[62:63], v[62:63], v[74:75]
	v_pk_mul_f32 v[68:69], v[68:69], v[116:117]
	v_lshl_add_u64 v[10:11], v[0:1], 0, v[52:53]
	v_lshl_add_u64 v[0:1], v[10:11], 0, s[22:23]
	v_add_co_u32_e32 v10, vcc, s27, v10
	v_mfma_f32_16x16x32_bf16 v[54:57], v[70:73], v[188:191], v[54:57]
	s_nop 0
	v_addc_co_u32_e32 v11, vcc, 0, v11, vcc
	s_nop 0
	v_add_f32_e32 v2, v2, v43
	v_add_f32_e32 v3, v3, v43
	v_add_f32_e32 v4, v4, v43
	v_add_f32_e32 v5, v5, v43
	v_mul_f32_e32 v2, v62, v2
	v_mul_f32_e32 v3, v63, v3
	v_mul_f32_e32 v4, v68, v4
	v_mul_f32_e32 v5, v69, v5
	v_cvt_pk_bf16_f32 v2, v2, v3
	v_cvt_pk_bf16_f32 v3, v4, v5
	v_pk_add_f32 v[4:5], v[66:67], 1.0 op_sel_hi:[1,0]
	flat_store_dwordx2 v[10:11], v[2:3] offset:1024
	v_rcp_f32_e32 v4, v4
	v_rcp_f32_e32 v5, v5
	v_pk_mul_f32 v[2:3], v[112:113], v[118:119]
	v_add_f32_e32 v6, v6, v43
	v_mul_f32_e32 v2, v2, v6
	v_add_f32_e32 v6, v7, v43
	v_mul_f32_e32 v3, v3, v6
	v_pk_mul_f32 v[4:5], v[4:5], v[120:121]
	v_cvt_pk_bf16_f32 v2, v2, v3
	v_add_f32_e32 v3, v8, v43
	v_mul_f32_e32 v3, v4, v3
	v_add_f32_e32 v4, v9, v43
	v_mul_f32_e32 v45, v5, v4
	v_lshlrev_b32_e32 v4, 16, v18
	v_and_b32_e32 v5, 0xffff0000, v18
	v_pk_mul_f32 v[6:7], v[4:5], v[4:5]
	v_lshlrev_b32_e32 v8, 16, v19
	v_pk_fma_f32 v[6:7], v[6:7], s[26:27], v[64:65] op_sel_hi:[1,0,0] neg_lo:[1,0,0] neg_hi:[1,0,0]
	v_and_b32_e32 v9, 0xffff0000, v19
	v_pk_mul_f32 v[6:7], v[6:7], v[4:5]
	v_pk_mul_f32 v[10:11], v[8:9], v[8:9]
	v_exp_f32_e32 v6, v6
	v_exp_f32_e32 v7, v7
	v_pk_fma_f32 v[10:11], v[10:11], s[26:27], v[64:65] op_sel_hi:[1,0,0] neg_lo:[1,0,0] neg_hi:[1,0,0]
	v_cvt_pk_bf16_f32 v3, v3, v45
	flat_store_dwordx2 v[0:1], v[2:3] offset:32
	v_pk_mul_f32 v[10:11], v[10:11], v[8:9]
	v_pk_add_f32 v[6:7], v[6:7], 1.0 op_sel_hi:[1,0]
	v_exp_f32_e32 v10, v10
	v_exp_f32_e32 v11, v11
	v_rcp_f32_e32 v6, v6
	v_rcp_f32_e32 v7, v7
	v_mfma_f32_16x16x32_bf16 v[58:61], v[164:167], v[184:187], v[58:61]
	v_add_f32_e64 v10, v10, 1.0
	v_add_f32_e64 v11, v11, 1.0
	v_pk_mul_f32 v[2:3], v[6:7], v[4:5]
	v_rcp_f32_e32 v10, v10
	v_rcp_f32_e32 v11, v11
	v_add_f32_e32 v6, v54, v43
	v_mul_f32_e32 v2, v2, v6
	v_add_f32_e32 v6, v55, v43
	v_mul_f32_e32 v3, v3, v6
	v_pk_mul_f32 v[4:5], v[10:11], v[8:9]
	v_cvt_pk_bf16_f32 v2, v2, v3
	v_add_f32_e32 v3, v56, v43
	v_mul_f32_e32 v3, v4, v3
	v_add_f32_e32 v4, v57, v43
	v_mul_f32_e32 v18, v5, v4
	v_lshlrev_b32_e32 v4, 16, v16
	v_and_b32_e32 v5, 0xffff0000, v16
	v_pk_mul_f32 v[6:7], v[4:5], v[4:5]
	v_lshlrev_b32_e32 v8, 16, v17
	v_pk_fma_f32 v[6:7], v[6:7], s[26:27], v[64:65] op_sel_hi:[1,0,0] neg_lo:[1,0,0] neg_hi:[1,0,0]
	v_and_b32_e32 v9, 0xffff0000, v17
	v_pk_mul_f32 v[6:7], v[6:7], v[4:5]
	v_pk_mul_f32 v[10:11], v[8:9], v[8:9]
	v_exp_f32_e32 v6, v6
	v_exp_f32_e32 v7, v7
	v_pk_fma_f32 v[10:11], v[10:11], s[26:27], v[64:65] op_sel_hi:[1,0,0] neg_lo:[1,0,0] neg_hi:[1,0,0]
	v_mfma_f32_16x16x32_bf16 v[58:61], v[152:155], v[188:191], v[58:61]
	v_mul_f32_e64 v10, v10, v8
	v_mul_f32_e64 v11, v11, v9
	v_pk_add_f32 v[6:7], v[6:7], 1.0 op_sel_hi:[1,0]
	v_exp_f32_e32 v10, v10
	v_exp_f32_e32 v11, v11
	v_rcp_f32_e32 v6, v6
	v_rcp_f32_e32 v7, v7
	v_cvt_pk_bf16_f32 v3, v3, v18
	v_pk_add_f32 v[10:11], v[10:11], 1.0 op_sel_hi:[1,0]
	flat_store_dwordx2 v[0:1], v[2:3] offset:64
	v_rcp_f32_e32 v10, v10
	v_rcp_f32_e32 v11, v11
	v_pk_mul_f32 v[2:3], v[6:7], v[4:5]
	v_add_f32_e32 v6, v58, v43
	v_mul_f32_e32 v2, v2, v6
	v_add_f32_e32 v6, v59, v43
	v_mul_f32_e32 v3, v3, v6
	v_pk_mul_f32 v[4:5], v[10:11], v[8:9]
	v_cvt_pk_bf16_f32 v2, v2, v3
	v_add_f32_e32 v3, v60, v43
	v_mul_f32_e32 v3, v4, v3
	v_add_f32_e32 v4, v61, v43
	v_mul_f32_e32 v4, v5, v4
	v_cvt_pk_bf16_f32 v3, v3, v4
	flat_store_dwordx2 v[0:1], v[2:3] offset:96
	s_cbranch_scc0 .LBB0_354
